# EpiResid epilogues: progressive waits (vmcnt(14) before each row pair) so residual add/convert/store starts as the first h-tile loads land instead of after all 16
# speedup vs baseline: 1.0055x; 1.0055x over previous
; __device__ __forceinline__ unsigned cvt_pk_bf16(float lo, float hi) { unsigned r; asm volatile("v_cvt_pk_bf16_f32 %0, %1, %2" : "=v"(r) : "v"(lo), "v"(hi)); return r; }
;     __device__ __forceinline__ void operator()(const f32x4 (&acc)[2][2][4][2], const Unit& u, int wr, int wc, int fr, int fq) const {
;         const int row0 = u.pm * BM + wr * 64 + fr, col0 = u.pn * BM + wc * 32 + 8 * fq;
;         u32x4 bw[2][4][2];
; #pragma unroll
;         for (int ai = 0; ai < 2; ++ai)
; #pragma unroll
;             for (int m = 0; m < 4; ++m)
; #pragma unroll
;                 for (int bj = 0; bj < 2; ++bj) bw[ai][m][bj] = *(const u32x4*)(hb + (size_t)(row0 + ai * HALF + m * 16) * 1024 + col0 + bj * HALF);
; #pragma unroll
;         for (int ai = 0; ai < 2; ++ai) {
; #pragma unroll
;             for (int m = 0; m < 4; ++m) { const int row = row0 + ai * HALF + m * 16; const size_t off = (size_t)row * 1024 + col0; float ss = 0.f;
; #pragma unroll
;                 for (int bj = 0; bj < 2; ++bj) {
;                     const u32x4 b = bw[ai][m][bj];
;                     const f32x4 b0 = (f32x4){__uint_as_float(b.x << 16), __uint_as_float(b.x & 0xffff0000u), __uint_as_float(b.y << 16), __uint_as_float(b.y & 0xffff0000u)};
;                     const f32x4 b1 = (f32x4){__uint_as_float(b.z << 16), __uint_as_float(b.z & 0xffff0000u), __uint_as_float(b.w << 16), __uint_as_float(b.w & 0xffff0000u)};
;                     const f32x4 v0 = acc[ai][bj][m][0] + b0, v1 = acc[ai][bj][m][1] + b1;
;                     ss += (v0[0] * v0[0] + v0[1] * v0[1]) + (v0[2] * v0[2] + v0[3] * v0[3]) + (v1[0] * v1[0] + v1[1] * v1[1]) + (v1[2] * v1[2] + v1[3] * v1[3]);
;                     u32x4 w; w.x = cvt_pk_bf16(v0[0], v0[1]); w.y = cvt_pk_bf16(v0[2], v0[3]); w.z = cvt_pk_bf16(v1[0], v1[1]); w.w = cvt_pk_bf16(v1[2], v1[3]);
;                     *(u32x4*)(hb + off + bj * HALF) = w; }
.LBB0_593:
	v_lshl_add_u32 v228, s67, 8, v248
	v_lshl_or_b32 v229, s6, 8, v250
	s_lshl_b32 s24, s6, 4
	s_lshl_b32 s86, s61, 2
	v_lshlrev_b32_e32 v240, 6, v228
	v_lshlrev_b32_e32 v228, 11, v228
	s_add_i32 s24, s24, s86
	v_lshl_add_u32 v228, v229, 1, v228
	v_add_u32_e32 v240, s24, v240
	global_load_dwordx4 v[112:115], v228, s[4:5]
	global_load_dwordx4 v[120:123], v228, s[4:5] offset:256
	v_add_u32_e32 v229, 0x8000, v228
	global_load_dwordx4 v[124:127], v229, s[4:5]
	global_load_dwordx4 v[128:131], v229, s[4:5] offset:256
	v_add_u32_e32 v229, 0x10000, v228
	global_load_dwordx4 v[136:139], v229, s[4:5]
	global_load_dwordx4 v[140:143], v229, s[4:5] offset:256
	v_add_u32_e32 v229, 0x18000, v228
	global_load_dwordx4 v[144:147], v229, s[4:5]
	global_load_dwordx4 v[156:159], v229, s[4:5] offset:256
	v_add_u32_e32 v229, 0x40000, v228
	global_load_dwordx4 v[160:163], v229, s[4:5]
	global_load_dwordx4 v[164:167], v229, s[4:5] offset:256
	v_add_u32_e32 v229, 0x48000, v228
	global_load_dwordx4 v[168:171], v229, s[4:5]
	global_load_dwordx4 v[172:175], v229, s[4:5] offset:256
	v_add_u32_e32 v229, 0x50000, v228
	global_load_dwordx4 v[176:179], v229, s[4:5]
	global_load_dwordx4 v[180:183], v229, s[4:5] offset:256
	v_add_u32_e32 v229, 0x58000, v228
	global_load_dwordx4 v[184:187], v229, s[4:5]
	global_load_dwordx4 v[188:191], v229, s[4:5] offset:256
	v_xor_b32_e32 v230, 16, v252
	v_xor_b32_e32 v231, 32, v252
	v_add_u32_e32 v241, 0x2000, v240
	v_lshlrev_b32_e32 v230, 2, v230
	v_lshlrev_b32_e32 v231, 2, v231
	s_waitcnt vmcnt(14)
	v_lshlrev_b32_e32 v194, 16, v112
	v_and_b32_e32 v195, 0xffff0000, v112
	v_lshlrev_b32_e32 v196, 16, v113
	v_and_b32_e32 v197, 0xffff0000, v113
	v_lshlrev_b32_e32 v208, 16, v114
	v_and_b32_e32 v209, 0xffff0000, v114
	v_lshlrev_b32_e32 v210, 16, v115
	v_and_b32_e32 v211, 0xffff0000, v115
	v_pk_add_f32 v[152:153], v[152:153], v[194:195]
	v_pk_add_f32 v[154:155], v[154:155], v[196:197]
	v_pk_add_f32 v[148:149], v[148:149], v[208:209]
	v_pk_add_f32 v[150:151], v[150:151], v[210:211]
	v_mul_f32_e32 v212, v152, v152
	v_fmac_f32_e32 v212, v153, v153
	v_fmac_f32_e32 v212, v154, v154
	v_fmac_f32_e32 v212, v155, v155
	v_fmac_f32_e32 v212, v148, v148
	v_fmac_f32_e32 v212, v149, v149
	v_fmac_f32_e32 v212, v150, v150
	v_fmac_f32_e32 v212, v151, v151
	v_cvt_pk_bf16_f32 v112, v152, v153
	v_cvt_pk_bf16_f32 v113, v154, v155
	v_cvt_pk_bf16_f32 v114, v148, v149
	v_cvt_pk_bf16_f32 v115, v150, v151
	global_store_dwordx4 v228, v[112:115], s[4:5]
	v_lshlrev_b32_e32 v194, 16, v120
	v_and_b32_e32 v195, 0xffff0000, v120
	v_lshlrev_b32_e32 v196, 16, v121
	v_and_b32_e32 v197, 0xffff0000, v121
	v_lshlrev_b32_e32 v208, 16, v122
	v_and_b32_e32 v209, 0xffff0000, v122
	v_lshlrev_b32_e32 v210, 16, v123
	v_and_b32_e32 v211, 0xffff0000, v123
	v_pk_add_f32 v[132:133], v[132:133], v[194:195]
	v_pk_add_f32 v[134:135], v[134:135], v[196:197]
	v_pk_add_f32 v[116:117], v[116:117], v[208:209]
	v_pk_add_f32 v[118:119], v[118:119], v[210:211]
	v_mul_f32_e32 v220, v132, v132
	v_fmac_f32_e32 v220, v133, v133
	v_fmac_f32_e32 v220, v134, v134
	v_fmac_f32_e32 v220, v135, v135
	v_fmac_f32_e32 v220, v116, v116
	v_fmac_f32_e32 v220, v117, v117
	v_fmac_f32_e32 v220, v118, v118
	v_fmac_f32_e32 v220, v119, v119
	v_cvt_pk_bf16_f32 v120, v132, v133
	v_cvt_pk_bf16_f32 v121, v134, v135
	v_cvt_pk_bf16_f32 v122, v116, v117
	v_cvt_pk_bf16_f32 v123, v118, v119
	global_store_dwordx4 v228, v[120:123], s[4:5] offset:256
	s_waitcnt vmcnt(14)
	v_add_u32_e32 v229, 0x8000, v228
	v_lshlrev_b32_e32 v194, 16, v124
	v_and_b32_e32 v195, 0xffff0000, v124
	v_lshlrev_b32_e32 v196, 16, v125
	v_and_b32_e32 v197, 0xffff0000, v125
	v_lshlrev_b32_e32 v208, 16, v126
	v_and_b32_e32 v209, 0xffff0000, v126
	v_lshlrev_b32_e32 v210, 16, v127
	v_and_b32_e32 v211, 0xffff0000, v127
	v_pk_add_f32 v[108:109], v[108:109], v[194:195]
	v_pk_add_f32 v[110:111], v[110:111], v[196:197]
	v_pk_add_f32 v[104:105], v[104:105], v[208:209]
	v_pk_add_f32 v[106:107], v[106:107], v[210:211]
	v_mul_f32_e32 v213, v108, v108
	v_fmac_f32_e32 v213, v109, v109
	v_fmac_f32_e32 v213, v110, v110
	v_fmac_f32_e32 v213, v111, v111
	v_fmac_f32_e32 v213, v104, v104
	v_fmac_f32_e32 v213, v105, v105
	v_fmac_f32_e32 v213, v106, v106
	v_fmac_f32_e32 v213, v107, v107
	v_cvt_pk_bf16_f32 v124, v108, v109
	v_cvt_pk_bf16_f32 v125, v110, v111
	v_cvt_pk_bf16_f32 v126, v104, v105
	v_cvt_pk_bf16_f32 v127, v106, v107
	global_store_dwordx4 v229, v[124:127], s[4:5]
	v_lshlrev_b32_e32 v194, 16, v128
	v_and_b32_e32 v195, 0xffff0000, v128
	v_lshlrev_b32_e32 v196, 16, v129
	v_and_b32_e32 v197, 0xffff0000, v129
	v_lshlrev_b32_e32 v208, 16, v130
	v_and_b32_e32 v209, 0xffff0000, v130
	v_lshlrev_b32_e32 v210, 16, v131
	v_and_b32_e32 v211, 0xffff0000, v131
	v_pk_add_f32 v[100:101], v[100:101], v[194:195]
	v_pk_add_f32 v[102:103], v[102:103], v[196:197]
	v_pk_add_f32 v[96:97], v[96:97], v[208:209]
	v_pk_add_f32 v[98:99], v[98:99], v[210:211]
	v_mul_f32_e32 v221, v100, v100
	v_fmac_f32_e32 v221, v101, v101
	v_fmac_f32_e32 v221, v102, v102
	v_fmac_f32_e32 v221, v103, v103
	v_fmac_f32_e32 v221, v96, v96
	v_fmac_f32_e32 v221, v97, v97
	v_fmac_f32_e32 v221, v98, v98
	v_fmac_f32_e32 v221, v99, v99
	v_cvt_pk_bf16_f32 v128, v100, v101
	v_cvt_pk_bf16_f32 v129, v102, v103
	v_cvt_pk_bf16_f32 v130, v96, v97
	v_cvt_pk_bf16_f32 v131, v98, v99
	global_store_dwordx4 v229, v[128:131], s[4:5] offset:256
	s_waitcnt vmcnt(14)
; __device__ __forceinline__ unsigned cvt_pk_bf16(float lo, float hi) { unsigned r; asm volatile("v_cvt_pk_bf16_f32 %0, %1, %2" : "=v"(r) : "v"(lo), "v"(hi)); return r; }
;     __device__ __forceinline__ void operator()(const f32x4 (&acc)[2][2][4][2], const Unit& u, int wr, int wc, int fr, int fq) const {
;     ...
;             for (int m = 0; m < 4; ++m) { const int row = row0 + ai * HALF + m * 16; const size_t off = (size_t)row * 1024 + col0; float ss = 0.f;
; #pragma unroll
;                 for (int bj = 0; bj < 2; ++bj) {
;                     const u32x4 b = bw[ai][m][bj];
;                     const f32x4 b0 = (f32x4){__uint_as_float(b.x << 16), __uint_as_float(b.x & 0xffff0000u), __uint_as_float(b.y << 16), __uint_as_float(b.y & 0xffff0000u)};
;                     const f32x4 b1 = (f32x4){__uint_as_float(b.z << 16), __uint_as_float(b.z & 0xffff0000u), __uint_as_float(b.w << 16), __uint_as_float(b.w & 0xffff0000u)};
;                     const f32x4 v0 = acc[ai][bj][m][0] + b0, v1 = acc[ai][bj][m][1] + b1;
;                     ss += (v0[0] * v0[0] + v0[1] * v0[1]) + (v0[2] * v0[2] + v0[3] * v0[3]) + (v1[0] * v1[0] + v1[1] * v1[1]) + (v1[2] * v1[2] + v1[3] * v1[3]);
;                     u32x4 w; w.x = cvt_pk_bf16(v0[0], v0[1]); w.y = cvt_pk_bf16(v0[2], v0[3]); w.z = cvt_pk_bf16(v1[0], v1[1]); w.w = cvt_pk_bf16(v1[2], v1[3]);
;                     *(u32x4*)(hb + off + bj * HALF) = w; }
	v_add_u32_e32 v229, 0x10000, v228
	v_lshlrev_b32_e32 v194, 16, v136
	v_and_b32_e32 v195, 0xffff0000, v136
	v_lshlrev_b32_e32 v196, 16, v137
	v_and_b32_e32 v197, 0xffff0000, v137
	v_lshlrev_b32_e32 v208, 16, v138
	v_and_b32_e32 v209, 0xffff0000, v138
	v_lshlrev_b32_e32 v210, 16, v139
	v_and_b32_e32 v211, 0xffff0000, v139
	v_pk_add_f32 v[92:93], v[92:93], v[194:195]
	v_pk_add_f32 v[94:95], v[94:95], v[196:197]
	v_pk_add_f32 v[88:89], v[88:89], v[208:209]
	v_pk_add_f32 v[90:91], v[90:91], v[210:211]
	v_mul_f32_e32 v214, v92, v92
	v_fmac_f32_e32 v214, v93, v93
	v_fmac_f32_e32 v214, v94, v94
	v_fmac_f32_e32 v214, v95, v95
	v_fmac_f32_e32 v214, v88, v88
	v_fmac_f32_e32 v214, v89, v89
	v_fmac_f32_e32 v214, v90, v90
	v_fmac_f32_e32 v214, v91, v91
	v_cvt_pk_bf16_f32 v136, v92, v93
	v_cvt_pk_bf16_f32 v137, v94, v95
	v_cvt_pk_bf16_f32 v138, v88, v89
	v_cvt_pk_bf16_f32 v139, v90, v91
	global_store_dwordx4 v229, v[136:139], s[4:5]
	v_lshlrev_b32_e32 v194, 16, v140
	v_and_b32_e32 v195, 0xffff0000, v140
	v_lshlrev_b32_e32 v196, 16, v141
	v_and_b32_e32 v197, 0xffff0000, v141
	v_lshlrev_b32_e32 v208, 16, v142
	v_and_b32_e32 v209, 0xffff0000, v142
	v_lshlrev_b32_e32 v210, 16, v143
	v_and_b32_e32 v211, 0xffff0000, v143
	v_pk_add_f32 v[84:85], v[84:85], v[194:195]
	v_pk_add_f32 v[86:87], v[86:87], v[196:197]
	v_pk_add_f32 v[80:81], v[80:81], v[208:209]
	v_pk_add_f32 v[82:83], v[82:83], v[210:211]
	v_mul_f32_e32 v222, v84, v84
	v_fmac_f32_e32 v222, v85, v85
	v_fmac_f32_e32 v222, v86, v86
	v_fmac_f32_e32 v222, v87, v87
	v_fmac_f32_e32 v222, v80, v80
	v_fmac_f32_e32 v222, v81, v81
	v_fmac_f32_e32 v222, v82, v82
	v_fmac_f32_e32 v222, v83, v83
	v_cvt_pk_bf16_f32 v140, v84, v85
	v_cvt_pk_bf16_f32 v141, v86, v87
	v_cvt_pk_bf16_f32 v142, v80, v81
	v_cvt_pk_bf16_f32 v143, v82, v83
	global_store_dwordx4 v229, v[140:143], s[4:5] offset:256
	s_waitcnt vmcnt(14)
	v_add_u32_e32 v229, 0x18000, v228
	v_lshlrev_b32_e32 v194, 16, v144
	v_and_b32_e32 v195, 0xffff0000, v144
	v_lshlrev_b32_e32 v196, 16, v145
	v_and_b32_e32 v197, 0xffff0000, v145
	v_lshlrev_b32_e32 v208, 16, v146
	v_and_b32_e32 v209, 0xffff0000, v146
	v_lshlrev_b32_e32 v210, 16, v147
	v_and_b32_e32 v211, 0xffff0000, v147
	v_pk_add_f32 v[76:77], v[76:77], v[194:195]
	v_pk_add_f32 v[78:79], v[78:79], v[196:197]
	v_pk_add_f32 v[72:73], v[72:73], v[208:209]
	v_pk_add_f32 v[74:75], v[74:75], v[210:211]
	v_mul_f32_e32 v215, v76, v76
	v_fmac_f32_e32 v215, v77, v77
	v_fmac_f32_e32 v215, v78, v78
	v_fmac_f32_e32 v215, v79, v79
	v_fmac_f32_e32 v215, v72, v72
	v_fmac_f32_e32 v215, v73, v73
	v_fmac_f32_e32 v215, v74, v74
	v_fmac_f32_e32 v215, v75, v75
	v_cvt_pk_bf16_f32 v144, v76, v77
	v_cvt_pk_bf16_f32 v145, v78, v79
	v_cvt_pk_bf16_f32 v146, v72, v73
	v_cvt_pk_bf16_f32 v147, v74, v75
	global_store_dwordx4 v229, v[144:147], s[4:5]
	v_lshlrev_b32_e32 v194, 16, v156
	v_and_b32_e32 v195, 0xffff0000, v156
	v_lshlrev_b32_e32 v196, 16, v157
	v_and_b32_e32 v197, 0xffff0000, v157
	v_lshlrev_b32_e32 v208, 16, v158
	v_and_b32_e32 v209, 0xffff0000, v158
	v_lshlrev_b32_e32 v210, 16, v159
	v_and_b32_e32 v211, 0xffff0000, v159
	v_pk_add_f32 v[68:69], v[68:69], v[194:195]
	v_pk_add_f32 v[70:71], v[70:71], v[196:197]
	v_pk_add_f32 v[64:65], v[64:65], v[208:209]
	v_pk_add_f32 v[66:67], v[66:67], v[210:211]
	v_mul_f32_e32 v223, v68, v68
	v_fmac_f32_e32 v223, v69, v69
	v_fmac_f32_e32 v223, v70, v70
	v_fmac_f32_e32 v223, v71, v71
	v_fmac_f32_e32 v223, v64, v64
	v_fmac_f32_e32 v223, v65, v65
	v_fmac_f32_e32 v223, v66, v66
	v_fmac_f32_e32 v223, v67, v67
	v_cvt_pk_bf16_f32 v156, v68, v69
	v_cvt_pk_bf16_f32 v157, v70, v71
	v_cvt_pk_bf16_f32 v158, v64, v65
	v_cvt_pk_bf16_f32 v159, v66, v67
	global_store_dwordx4 v229, v[156:159], s[4:5] offset:256
	s_waitcnt vmcnt(14)
	v_add_u32_e32 v229, 0x40000, v228
	v_lshlrev_b32_e32 v194, 16, v160
	v_and_b32_e32 v195, 0xffff0000, v160
	v_lshlrev_b32_e32 v196, 16, v161
	v_and_b32_e32 v197, 0xffff0000, v161
	v_lshlrev_b32_e32 v208, 16, v162
	v_and_b32_e32 v209, 0xffff0000, v162
	v_lshlrev_b32_e32 v210, 16, v163
	v_and_b32_e32 v211, 0xffff0000, v163
	v_pk_add_f32 v[60:61], v[60:61], v[194:195]
	v_pk_add_f32 v[62:63], v[62:63], v[196:197]
	v_pk_add_f32 v[56:57], v[56:57], v[208:209]
	v_pk_add_f32 v[58:59], v[58:59], v[210:211]
	v_mul_f32_e32 v216, v60, v60
	v_fmac_f32_e32 v216, v61, v61
	v_fmac_f32_e32 v216, v62, v62
	v_fmac_f32_e32 v216, v63, v63
	v_fmac_f32_e32 v216, v56, v56
	v_fmac_f32_e32 v216, v57, v57
	v_fmac_f32_e32 v216, v58, v58
	v_fmac_f32_e32 v216, v59, v59
	v_cvt_pk_bf16_f32 v160, v60, v61
	v_cvt_pk_bf16_f32 v161, v62, v63
	v_cvt_pk_bf16_f32 v162, v56, v57
	v_cvt_pk_bf16_f32 v163, v58, v59
	global_store_dwordx4 v229, v[160:163], s[4:5]
	v_lshlrev_b32_e32 v194, 16, v164
	v_and_b32_e32 v195, 0xffff0000, v164
	v_lshlrev_b32_e32 v196, 16, v165
	v_and_b32_e32 v197, 0xffff0000, v165
	v_lshlrev_b32_e32 v208, 16, v166
	v_and_b32_e32 v209, 0xffff0000, v166
	v_lshlrev_b32_e32 v210, 16, v167
	v_and_b32_e32 v211, 0xffff0000, v167
	v_pk_add_f32 v[52:53], v[52:53], v[194:195]
	v_pk_add_f32 v[54:55], v[54:55], v[196:197]
	v_pk_add_f32 v[48:49], v[48:49], v[208:209]
	v_pk_add_f32 v[50:51], v[50:51], v[210:211]
	v_mul_f32_e32 v224, v52, v52
	v_fmac_f32_e32 v224, v53, v53
	v_fmac_f32_e32 v224, v54, v54
	v_fmac_f32_e32 v224, v55, v55
	v_fmac_f32_e32 v224, v48, v48
	v_fmac_f32_e32 v224, v49, v49
	v_fmac_f32_e32 v224, v50, v50
	v_fmac_f32_e32 v224, v51, v51
	v_cvt_pk_bf16_f32 v164, v52, v53
	v_cvt_pk_bf16_f32 v165, v54, v55
	v_cvt_pk_bf16_f32 v166, v48, v49
	v_cvt_pk_bf16_f32 v167, v50, v51
	global_store_dwordx4 v229, v[164:167], s[4:5] offset:256
	s_waitcnt vmcnt(14)
; __device__ __forceinline__ unsigned cvt_pk_bf16(float lo, float hi) { unsigned r; asm volatile("v_cvt_pk_bf16_f32 %0, %1, %2" : "=v"(r) : "v"(lo), "v"(hi)); return r; }
;     __device__ __forceinline__ void operator()(const f32x4 (&acc)[2][2][4][2], const Unit& u, int wr, int wc, int fr, int fq) const {
;     ...
;             for (int m = 0; m < 4; ++m) { const int row = row0 + ai * HALF + m * 16; const size_t off = (size_t)row * 1024 + col0; float ss = 0.f;
; #pragma unroll
;                 for (int bj = 0; bj < 2; ++bj) {
;                     const u32x4 b = bw[ai][m][bj];
;                     const f32x4 b0 = (f32x4){__uint_as_float(b.x << 16), __uint_as_float(b.x & 0xffff0000u), __uint_as_float(b.y << 16), __uint_as_float(b.y & 0xffff0000u)};
;                     const f32x4 b1 = (f32x4){__uint_as_float(b.z << 16), __uint_as_float(b.z & 0xffff0000u), __uint_as_float(b.w << 16), __uint_as_float(b.w & 0xffff0000u)};
;                     const f32x4 v0 = acc[ai][bj][m][0] + b0, v1 = acc[ai][bj][m][1] + b1;
;                     ss += (v0[0] * v0[0] + v0[1] * v0[1]) + (v0[2] * v0[2] + v0[3] * v0[3]) + (v1[0] * v1[0] + v1[1] * v1[1]) + (v1[2] * v1[2] + v1[3] * v1[3]);
;                     u32x4 w; w.x = cvt_pk_bf16(v0[0], v0[1]); w.y = cvt_pk_bf16(v0[2], v0[3]); w.z = cvt_pk_bf16(v1[0], v1[1]); w.w = cvt_pk_bf16(v1[2], v1[3]);
;                     *(u32x4*)(hb + off + bj * HALF) = w; }
	v_add_u32_e32 v229, 0x48000, v228
	v_lshlrev_b32_e32 v194, 16, v168
	v_and_b32_e32 v195, 0xffff0000, v168
	v_lshlrev_b32_e32 v196, 16, v169
	v_and_b32_e32 v197, 0xffff0000, v169
	v_lshlrev_b32_e32 v208, 16, v170
	v_and_b32_e32 v209, 0xffff0000, v170
	v_lshlrev_b32_e32 v210, 16, v171
	v_and_b32_e32 v211, 0xffff0000, v171
	v_pk_add_f32 v[44:45], v[44:45], v[194:195]
	v_pk_add_f32 v[46:47], v[46:47], v[196:197]
	v_pk_add_f32 v[40:41], v[40:41], v[208:209]
	v_pk_add_f32 v[42:43], v[42:43], v[210:211]
	v_mul_f32_e32 v217, v44, v44
	v_fmac_f32_e32 v217, v45, v45
	v_fmac_f32_e32 v217, v46, v46
	v_fmac_f32_e32 v217, v47, v47
	v_fmac_f32_e32 v217, v40, v40
	v_fmac_f32_e32 v217, v41, v41
	v_fmac_f32_e32 v217, v42, v42
	v_fmac_f32_e32 v217, v43, v43
	v_cvt_pk_bf16_f32 v168, v44, v45
	v_cvt_pk_bf16_f32 v169, v46, v47
	v_cvt_pk_bf16_f32 v170, v40, v41
	v_cvt_pk_bf16_f32 v171, v42, v43
	global_store_dwordx4 v229, v[168:171], s[4:5]
	v_lshlrev_b32_e32 v194, 16, v172
	v_and_b32_e32 v195, 0xffff0000, v172
	v_lshlrev_b32_e32 v196, 16, v173
	v_and_b32_e32 v197, 0xffff0000, v173
	v_lshlrev_b32_e32 v208, 16, v174
	v_and_b32_e32 v209, 0xffff0000, v174
	v_lshlrev_b32_e32 v210, 16, v175
	v_and_b32_e32 v211, 0xffff0000, v175
	v_pk_add_f32 v[36:37], v[36:37], v[194:195]
	v_pk_add_f32 v[38:39], v[38:39], v[196:197]
	v_pk_add_f32 v[32:33], v[32:33], v[208:209]
	v_pk_add_f32 v[34:35], v[34:35], v[210:211]
	v_mul_f32_e32 v225, v36, v36
	v_fmac_f32_e32 v225, v37, v37
	v_fmac_f32_e32 v225, v38, v38
	v_fmac_f32_e32 v225, v39, v39
	v_fmac_f32_e32 v225, v32, v32
	v_fmac_f32_e32 v225, v33, v33
	v_fmac_f32_e32 v225, v34, v34
	v_fmac_f32_e32 v225, v35, v35
	v_cvt_pk_bf16_f32 v172, v36, v37
	v_cvt_pk_bf16_f32 v173, v38, v39
	v_cvt_pk_bf16_f32 v174, v32, v33
	v_cvt_pk_bf16_f32 v175, v34, v35
	global_store_dwordx4 v229, v[172:175], s[4:5] offset:256
	s_waitcnt vmcnt(14)
	v_add_u32_e32 v229, 0x50000, v228
	v_lshlrev_b32_e32 v194, 16, v176
	v_and_b32_e32 v195, 0xffff0000, v176
	v_lshlrev_b32_e32 v196, 16, v177
	v_and_b32_e32 v197, 0xffff0000, v177
	v_lshlrev_b32_e32 v208, 16, v178
	v_and_b32_e32 v209, 0xffff0000, v178
	v_lshlrev_b32_e32 v210, 16, v179
	v_and_b32_e32 v211, 0xffff0000, v179
	v_pk_add_f32 v[28:29], v[28:29], v[194:195]
	v_pk_add_f32 v[30:31], v[30:31], v[196:197]
	v_pk_add_f32 v[24:25], v[24:25], v[208:209]
	v_pk_add_f32 v[26:27], v[26:27], v[210:211]
	v_mul_f32_e32 v218, v28, v28
	v_fmac_f32_e32 v218, v29, v29
	v_fmac_f32_e32 v218, v30, v30
	v_fmac_f32_e32 v218, v31, v31
	v_fmac_f32_e32 v218, v24, v24
	v_fmac_f32_e32 v218, v25, v25
	v_fmac_f32_e32 v218, v26, v26
	v_fmac_f32_e32 v218, v27, v27
	v_cvt_pk_bf16_f32 v176, v28, v29
	v_cvt_pk_bf16_f32 v177, v30, v31
	v_cvt_pk_bf16_f32 v178, v24, v25
	v_cvt_pk_bf16_f32 v179, v26, v27
	global_store_dwordx4 v229, v[176:179], s[4:5]
	v_lshlrev_b32_e32 v194, 16, v180
	v_and_b32_e32 v195, 0xffff0000, v180
	v_lshlrev_b32_e32 v196, 16, v181
	v_and_b32_e32 v197, 0xffff0000, v181
	v_lshlrev_b32_e32 v208, 16, v182
	v_and_b32_e32 v209, 0xffff0000, v182
	v_lshlrev_b32_e32 v210, 16, v183
	v_and_b32_e32 v211, 0xffff0000, v183
	v_pk_add_f32 v[20:21], v[20:21], v[194:195]
	v_pk_add_f32 v[22:23], v[22:23], v[196:197]
	v_pk_add_f32 v[16:17], v[16:17], v[208:209]
	v_pk_add_f32 v[18:19], v[18:19], v[210:211]
	v_mul_f32_e32 v226, v20, v20
	v_fmac_f32_e32 v226, v21, v21
	v_fmac_f32_e32 v226, v22, v22
	v_fmac_f32_e32 v226, v23, v23
	v_fmac_f32_e32 v226, v16, v16
	v_fmac_f32_e32 v226, v17, v17
	v_fmac_f32_e32 v226, v18, v18
	v_fmac_f32_e32 v226, v19, v19
	v_cvt_pk_bf16_f32 v180, v20, v21
	v_cvt_pk_bf16_f32 v181, v22, v23
	v_cvt_pk_bf16_f32 v182, v16, v17
	v_cvt_pk_bf16_f32 v183, v18, v19
	global_store_dwordx4 v229, v[180:183], s[4:5] offset:256
	s_waitcnt vmcnt(14)
; __device__ __forceinline__ unsigned cvt_pk_bf16(float lo, float hi) { unsigned r; asm volatile("v_cvt_pk_bf16_f32 %0, %1, %2" : "=v"(r) : "v"(lo), "v"(hi)); return r; }
;     __device__ __forceinline__ void operator()(const f32x4 (&acc)[2][2][4][2], const Unit& u, int wr, int wc, int fr, int fq) const {
;     ...
;             for (int m = 0; m < 4; ++m) { const int row = row0 + ai * HALF + m * 16; const size_t off = (size_t)row * 1024 + col0; float ss = 0.f;
; #pragma unroll
;                 for (int bj = 0; bj < 2; ++bj) {
;                     const u32x4 b = bw[ai][m][bj];
;                     const f32x4 b0 = (f32x4){__uint_as_float(b.x << 16), __uint_as_float(b.x & 0xffff0000u), __uint_as_float(b.y << 16), __uint_as_float(b.y & 0xffff0000u)};
;                     const f32x4 b1 = (f32x4){__uint_as_float(b.z << 16), __uint_as_float(b.z & 0xffff0000u), __uint_as_float(b.w << 16), __uint_as_float(b.w & 0xffff0000u)};
;                     const f32x4 v0 = acc[ai][bj][m][0] + b0, v1 = acc[ai][bj][m][1] + b1;
;                     ss += (v0[0] * v0[0] + v0[1] * v0[1]) + (v0[2] * v0[2] + v0[3] * v0[3]) + (v1[0] * v1[0] + v1[1] * v1[1]) + (v1[2] * v1[2] + v1[3] * v1[3]);
;                     u32x4 w; w.x = cvt_pk_bf16(v0[0], v0[1]); w.y = cvt_pk_bf16(v0[2], v0[3]); w.z = cvt_pk_bf16(v1[0], v1[1]); w.w = cvt_pk_bf16(v1[2], v1[3]);
;                     *(u32x4*)(hb + off + bj * HALF) = w; }
;                 ss += __shfl_xor(ss, 16); ss += __shfl_xor(ss, 32);
;                 if (fq == 0) slots[(size_t)row * 16 + u.pn * 4 + wc] = ss; }
	v_add_u32_e32 v229, 0x58000, v228
	v_lshlrev_b32_e32 v194, 16, v184
	v_and_b32_e32 v195, 0xffff0000, v184
	v_lshlrev_b32_e32 v196, 16, v185
	v_and_b32_e32 v197, 0xffff0000, v185
	v_lshlrev_b32_e32 v208, 16, v186
	v_and_b32_e32 v209, 0xffff0000, v186
	v_lshlrev_b32_e32 v210, 16, v187
	v_and_b32_e32 v211, 0xffff0000, v187
	v_pk_add_f32 v[12:13], v[12:13], v[194:195]
	v_pk_add_f32 v[14:15], v[14:15], v[196:197]
	v_pk_add_f32 v[8:9], v[8:9], v[208:209]
	v_pk_add_f32 v[10:11], v[10:11], v[210:211]
	v_mul_f32_e32 v219, v12, v12
	v_fmac_f32_e32 v219, v13, v13
	v_fmac_f32_e32 v219, v14, v14
	v_fmac_f32_e32 v219, v15, v15
	v_fmac_f32_e32 v219, v8, v8
	v_fmac_f32_e32 v219, v9, v9
	v_fmac_f32_e32 v219, v10, v10
	v_fmac_f32_e32 v219, v11, v11
	v_cvt_pk_bf16_f32 v184, v12, v13
	v_cvt_pk_bf16_f32 v185, v14, v15
	v_cvt_pk_bf16_f32 v186, v8, v9
	v_cvt_pk_bf16_f32 v187, v10, v11
	global_store_dwordx4 v229, v[184:187], s[4:5]
	v_lshlrev_b32_e32 v194, 16, v188
	v_and_b32_e32 v195, 0xffff0000, v188
	v_lshlrev_b32_e32 v196, 16, v189
	v_and_b32_e32 v197, 0xffff0000, v189
	v_lshlrev_b32_e32 v208, 16, v190
	v_and_b32_e32 v209, 0xffff0000, v190
	v_lshlrev_b32_e32 v210, 16, v191
	v_and_b32_e32 v211, 0xffff0000, v191
	v_pk_add_f32 v[4:5], v[4:5], v[194:195]
	v_pk_add_f32 v[6:7], v[6:7], v[196:197]
	v_pk_add_f32 v[0:1], v[0:1], v[208:209]
	v_pk_add_f32 v[2:3], v[2:3], v[210:211]
	v_mul_f32_e32 v227, v4, v4
	v_fmac_f32_e32 v227, v5, v5
	v_fmac_f32_e32 v227, v6, v6
	v_fmac_f32_e32 v227, v7, v7
	v_fmac_f32_e32 v227, v0, v0
	v_fmac_f32_e32 v227, v1, v1
	v_fmac_f32_e32 v227, v2, v2
	v_fmac_f32_e32 v227, v3, v3
	v_cvt_pk_bf16_f32 v188, v4, v5
	v_cvt_pk_bf16_f32 v189, v6, v7
	v_cvt_pk_bf16_f32 v190, v0, v1
	v_cvt_pk_bf16_f32 v191, v2, v3
	global_store_dwordx4 v229, v[188:191], s[4:5] offset:256
	v_add_f32_e32 v212, v212, v220
	v_add_f32_e32 v213, v213, v221
	v_add_f32_e32 v214, v214, v222
	v_add_f32_e32 v215, v215, v223
	v_add_f32_e32 v216, v216, v224
	v_add_f32_e32 v217, v217, v225
	v_add_f32_e32 v218, v218, v226
	v_add_f32_e32 v219, v219, v227
	ds_bpermute_b32 v232, v230, v212
	ds_bpermute_b32 v233, v230, v213
	ds_bpermute_b32 v234, v230, v214
	ds_bpermute_b32 v235, v230, v215
	ds_bpermute_b32 v236, v230, v216
	ds_bpermute_b32 v237, v230, v217
	ds_bpermute_b32 v238, v230, v218
	ds_bpermute_b32 v239, v230, v219
	s_waitcnt lgkmcnt(0)
	v_add_f32_e32 v212, v212, v232
	v_add_f32_e32 v213, v213, v233
	v_add_f32_e32 v214, v214, v234
	v_add_f32_e32 v215, v215, v235
	v_add_f32_e32 v216, v216, v236
	v_add_f32_e32 v217, v217, v237
	v_add_f32_e32 v218, v218, v238
	v_add_f32_e32 v219, v219, v239
	ds_bpermute_b32 v232, v231, v212
	ds_bpermute_b32 v233, v231, v213
	ds_bpermute_b32 v234, v231, v214
	ds_bpermute_b32 v235, v231, v215
	ds_bpermute_b32 v236, v231, v216
	ds_bpermute_b32 v237, v231, v217
	ds_bpermute_b32 v238, v231, v218
	ds_bpermute_b32 v239, v231, v219
	s_waitcnt lgkmcnt(0)
	v_add_f32_e32 v212, v212, v232
	v_add_f32_e32 v213, v213, v233
	v_add_f32_e32 v214, v214, v234
	v_add_f32_e32 v215, v215, v235
	v_add_f32_e32 v216, v216, v236
	v_add_f32_e32 v217, v217, v237
	v_add_f32_e32 v218, v218, v238
	v_add_f32_e32 v219, v219, v239
	s_and_saveexec_b64 s[24:25], s[40:41]
	global_store_dword v240, v212, s[10:11]
	global_store_dword v240, v213, s[10:11] offset:1024
	global_store_dword v240, v214, s[10:11] offset:2048
	global_store_dword v240, v215, s[10:11] offset:3072
	global_store_dword v241, v216, s[10:11]
	global_store_dword v241, v217, s[10:11] offset:1024
	global_store_dword v241, v218, s[10:11] offset:2048
	global_store_dword v241, v219, s[10:11] offset:3072
	s_or_b64 exec, exec, s[24:25]
	s_and_b64 vcc, exec, s[42:43]
	s_mov_b64 s[22:23], -1
	s_cbranch_vccnz .LBB0_580
	s_andn2_b64 vcc, exec, s[0:1]
	s_cbranch_vccnz .LBB0_579
	s_barrier
	s_branch .LBB0_579

; __device__ __forceinline__ unsigned cvt_pk_bf16(float lo, float hi) { unsigned r; asm volatile("v_cvt_pk_bf16_f32 %0, %1, %2" : "=v"(r) : "v"(lo), "v"(hi)); return r; }
;     __device__ __forceinline__ void operator()(const f32x4 (&acc)[2][2][4][2], const Unit& u, int wr, int wc, int fr, int fq) const {
;         const int row0 = u.pm * BM + wr * 64 + fr, col0 = u.pn * BM + wc * 32 + 8 * fq;
;         u32x4 bw[2][4][2];
; #pragma unroll
;         for (int ai = 0; ai < 2; ++ai)
; #pragma unroll
;             for (int m = 0; m < 4; ++m)
; #pragma unroll
;                 for (int bj = 0; bj < 2; ++bj) bw[ai][m][bj] = *(const u32x4*)(hb + (size_t)(row0 + ai * HALF + m * 16) * 1024 + col0 + bj * HALF);
; #pragma unroll
;         for (int ai = 0; ai < 2; ++ai) {
; #pragma unroll
;             for (int m = 0; m < 4; ++m) { const int row = row0 + ai * HALF + m * 16; const size_t off = (size_t)row * 1024 + col0; float ss = 0.f;
; #pragma unroll
;                 for (int bj = 0; bj < 2; ++bj) {
;                     const u32x4 b = bw[ai][m][bj];
;                     const f32x4 b0 = (f32x4){__uint_as_float(b.x << 16), __uint_as_float(b.x & 0xffff0000u), __uint_as_float(b.y << 16), __uint_as_float(b.y & 0xffff0000u)};
;                     const f32x4 b1 = (f32x4){__uint_as_float(b.z << 16), __uint_as_float(b.z & 0xffff0000u), __uint_as_float(b.w << 16), __uint_as_float(b.w & 0xffff0000u)};
;                     const f32x4 v0 = acc[ai][bj][m][0] + b0, v1 = acc[ai][bj][m][1] + b1;
;                     ss += (v0[0] * v0[0] + v0[1] * v0[1]) + (v0[2] * v0[2] + v0[3] * v0[3]) + (v1[0] * v1[0] + v1[1] * v1[1]) + (v1[2] * v1[2] + v1[3] * v1[3]);
;                     u32x4 w; w.x = cvt_pk_bf16(v0[0], v0[1]); w.y = cvt_pk_bf16(v0[2], v0[3]); w.z = cvt_pk_bf16(v1[0], v1[1]); w.w = cvt_pk_bf16(v1[2], v1[3]);
;                     *(u32x4*)(hb + off + bj * HALF) = w; }
.LBB0_1034:
	v_lshl_add_u32 v228, s71, 8, v248
	v_lshl_or_b32 v229, s6, 8, v250
	s_lshl_b32 s20, s6, 4
	s_lshl_b32 s86, s61, 2
	v_lshlrev_b32_e32 v240, 6, v228
	v_lshlrev_b32_e32 v228, 11, v228
	s_add_i32 s20, s20, s86
	v_lshl_add_u32 v228, v229, 1, v228
	v_add_u32_e32 v240, s20, v240
	global_load_dwordx4 v[112:115], v228, s[4:5]
	global_load_dwordx4 v[120:123], v228, s[4:5] offset:256
	v_add_u32_e32 v229, 0x8000, v228
	global_load_dwordx4 v[124:127], v229, s[4:5]
	global_load_dwordx4 v[128:131], v229, s[4:5] offset:256
	v_add_u32_e32 v229, 0x10000, v228
	global_load_dwordx4 v[136:139], v229, s[4:5]
	global_load_dwordx4 v[140:143], v229, s[4:5] offset:256
	v_add_u32_e32 v229, 0x18000, v228
	global_load_dwordx4 v[144:147], v229, s[4:5]
	global_load_dwordx4 v[156:159], v229, s[4:5] offset:256
	v_add_u32_e32 v229, 0x40000, v228
	global_load_dwordx4 v[160:163], v229, s[4:5]
	global_load_dwordx4 v[164:167], v229, s[4:5] offset:256
	v_add_u32_e32 v229, 0x48000, v228
	global_load_dwordx4 v[168:171], v229, s[4:5]
	global_load_dwordx4 v[172:175], v229, s[4:5] offset:256
	v_add_u32_e32 v229, 0x50000, v228
	global_load_dwordx4 v[176:179], v229, s[4:5]
	global_load_dwordx4 v[180:183], v229, s[4:5] offset:256
	v_add_u32_e32 v229, 0x58000, v228
	global_load_dwordx4 v[184:187], v229, s[4:5]
	global_load_dwordx4 v[188:191], v229, s[4:5] offset:256
	v_xor_b32_e32 v230, 16, v252
	v_xor_b32_e32 v231, 32, v252
	v_add_u32_e32 v241, 0x2000, v240
	v_lshlrev_b32_e32 v230, 2, v230
	v_lshlrev_b32_e32 v231, 2, v231
	s_waitcnt vmcnt(14)
	v_lshlrev_b32_e32 v194, 16, v112
	v_and_b32_e32 v195, 0xffff0000, v112
	v_lshlrev_b32_e32 v196, 16, v113
	v_and_b32_e32 v197, 0xffff0000, v113
	v_lshlrev_b32_e32 v208, 16, v114
	v_and_b32_e32 v209, 0xffff0000, v114
	v_lshlrev_b32_e32 v210, 16, v115
	v_and_b32_e32 v211, 0xffff0000, v115
	v_pk_add_f32 v[152:153], v[152:153], v[194:195]
	v_pk_add_f32 v[154:155], v[154:155], v[196:197]
	v_pk_add_f32 v[148:149], v[148:149], v[208:209]
	v_pk_add_f32 v[150:151], v[150:151], v[210:211]
	v_mul_f32_e32 v212, v152, v152
	v_fmac_f32_e32 v212, v153, v153
	v_fmac_f32_e32 v212, v154, v154
	v_fmac_f32_e32 v212, v155, v155
	v_fmac_f32_e32 v212, v148, v148
	v_fmac_f32_e32 v212, v149, v149
	v_fmac_f32_e32 v212, v150, v150
	v_fmac_f32_e32 v212, v151, v151
	v_cvt_pk_bf16_f32 v112, v152, v153
	v_cvt_pk_bf16_f32 v113, v154, v155
	v_cvt_pk_bf16_f32 v114, v148, v149
	v_cvt_pk_bf16_f32 v115, v150, v151
	global_store_dwordx4 v228, v[112:115], s[4:5]
	v_lshlrev_b32_e32 v194, 16, v120
	v_and_b32_e32 v195, 0xffff0000, v120
	v_lshlrev_b32_e32 v196, 16, v121
	v_and_b32_e32 v197, 0xffff0000, v121
	v_lshlrev_b32_e32 v208, 16, v122
	v_and_b32_e32 v209, 0xffff0000, v122
	v_lshlrev_b32_e32 v210, 16, v123
	v_and_b32_e32 v211, 0xffff0000, v123
	v_pk_add_f32 v[132:133], v[132:133], v[194:195]
	v_pk_add_f32 v[134:135], v[134:135], v[196:197]
	v_pk_add_f32 v[116:117], v[116:117], v[208:209]
	v_pk_add_f32 v[118:119], v[118:119], v[210:211]
	v_mul_f32_e32 v220, v132, v132
	v_fmac_f32_e32 v220, v133, v133
	v_fmac_f32_e32 v220, v134, v134
	v_fmac_f32_e32 v220, v135, v135
	v_fmac_f32_e32 v220, v116, v116
	v_fmac_f32_e32 v220, v117, v117
	v_fmac_f32_e32 v220, v118, v118
	v_fmac_f32_e32 v220, v119, v119
	v_cvt_pk_bf16_f32 v120, v132, v133
	v_cvt_pk_bf16_f32 v121, v134, v135
	v_cvt_pk_bf16_f32 v122, v116, v117
	v_cvt_pk_bf16_f32 v123, v118, v119
	global_store_dwordx4 v228, v[120:123], s[4:5] offset:256
	s_waitcnt vmcnt(14)
	v_add_u32_e32 v229, 0x8000, v228
	v_lshlrev_b32_e32 v194, 16, v124
	v_and_b32_e32 v195, 0xffff0000, v124
	v_lshlrev_b32_e32 v196, 16, v125
	v_and_b32_e32 v197, 0xffff0000, v125
	v_lshlrev_b32_e32 v208, 16, v126
	v_and_b32_e32 v209, 0xffff0000, v126
	v_lshlrev_b32_e32 v210, 16, v127
	v_and_b32_e32 v211, 0xffff0000, v127
	v_pk_add_f32 v[108:109], v[108:109], v[194:195]
	v_pk_add_f32 v[110:111], v[110:111], v[196:197]
	v_pk_add_f32 v[104:105], v[104:105], v[208:209]
	v_pk_add_f32 v[106:107], v[106:107], v[210:211]
	v_mul_f32_e32 v213, v108, v108
	v_fmac_f32_e32 v213, v109, v109
	v_fmac_f32_e32 v213, v110, v110
	v_fmac_f32_e32 v213, v111, v111
	v_fmac_f32_e32 v213, v104, v104
	v_fmac_f32_e32 v213, v105, v105
	v_fmac_f32_e32 v213, v106, v106
	v_fmac_f32_e32 v213, v107, v107
	v_cvt_pk_bf16_f32 v124, v108, v109
	v_cvt_pk_bf16_f32 v125, v110, v111
	v_cvt_pk_bf16_f32 v126, v104, v105
	v_cvt_pk_bf16_f32 v127, v106, v107
	global_store_dwordx4 v229, v[124:127], s[4:5]
	v_lshlrev_b32_e32 v194, 16, v128
	v_and_b32_e32 v195, 0xffff0000, v128
	v_lshlrev_b32_e32 v196, 16, v129
	v_and_b32_e32 v197, 0xffff0000, v129
	v_lshlrev_b32_e32 v208, 16, v130
	v_and_b32_e32 v209, 0xffff0000, v130
	v_lshlrev_b32_e32 v210, 16, v131
	v_and_b32_e32 v211, 0xffff0000, v131
	v_pk_add_f32 v[100:101], v[100:101], v[194:195]
	v_pk_add_f32 v[102:103], v[102:103], v[196:197]
	v_pk_add_f32 v[96:97], v[96:97], v[208:209]
	v_pk_add_f32 v[98:99], v[98:99], v[210:211]
	v_mul_f32_e32 v221, v100, v100
	v_fmac_f32_e32 v221, v101, v101
	v_fmac_f32_e32 v221, v102, v102
	v_fmac_f32_e32 v221, v103, v103
	v_fmac_f32_e32 v221, v96, v96
	v_fmac_f32_e32 v221, v97, v97
	v_fmac_f32_e32 v221, v98, v98
	v_fmac_f32_e32 v221, v99, v99
	v_cvt_pk_bf16_f32 v128, v100, v101
	v_cvt_pk_bf16_f32 v129, v102, v103
	v_cvt_pk_bf16_f32 v130, v96, v97
	v_cvt_pk_bf16_f32 v131, v98, v99
	global_store_dwordx4 v229, v[128:131], s[4:5] offset:256
	s_waitcnt vmcnt(14)
; __device__ __forceinline__ unsigned cvt_pk_bf16(float lo, float hi) { unsigned r; asm volatile("v_cvt_pk_bf16_f32 %0, %1, %2" : "=v"(r) : "v"(lo), "v"(hi)); return r; }
;     __device__ __forceinline__ void operator()(const f32x4 (&acc)[2][2][4][2], const Unit& u, int wr, int wc, int fr, int fq) const {
;     ...
;             for (int m = 0; m < 4; ++m) { const int row = row0 + ai * HALF + m * 16; const size_t off = (size_t)row * 1024 + col0; float ss = 0.f;
; #pragma unroll
;                 for (int bj = 0; bj < 2; ++bj) {
;                     const u32x4 b = bw[ai][m][bj];
;                     const f32x4 b0 = (f32x4){__uint_as_float(b.x << 16), __uint_as_float(b.x & 0xffff0000u), __uint_as_float(b.y << 16), __uint_as_float(b.y & 0xffff0000u)};
;                     const f32x4 b1 = (f32x4){__uint_as_float(b.z << 16), __uint_as_float(b.z & 0xffff0000u), __uint_as_float(b.w << 16), __uint_as_float(b.w & 0xffff0000u)};
;                     const f32x4 v0 = acc[ai][bj][m][0] + b0, v1 = acc[ai][bj][m][1] + b1;
;                     ss += (v0[0] * v0[0] + v0[1] * v0[1]) + (v0[2] * v0[2] + v0[3] * v0[3]) + (v1[0] * v1[0] + v1[1] * v1[1]) + (v1[2] * v1[2] + v1[3] * v1[3]);
;                     u32x4 w; w.x = cvt_pk_bf16(v0[0], v0[1]); w.y = cvt_pk_bf16(v0[2], v0[3]); w.z = cvt_pk_bf16(v1[0], v1[1]); w.w = cvt_pk_bf16(v1[2], v1[3]);
;                     *(u32x4*)(hb + off + bj * HALF) = w; }
	v_add_u32_e32 v229, 0x10000, v228
	v_lshlrev_b32_e32 v194, 16, v136
	v_and_b32_e32 v195, 0xffff0000, v136
	v_lshlrev_b32_e32 v196, 16, v137
	v_and_b32_e32 v197, 0xffff0000, v137
	v_lshlrev_b32_e32 v208, 16, v138
	v_and_b32_e32 v209, 0xffff0000, v138
	v_lshlrev_b32_e32 v210, 16, v139
	v_and_b32_e32 v211, 0xffff0000, v139
	v_pk_add_f32 v[92:93], v[92:93], v[194:195]
	v_pk_add_f32 v[94:95], v[94:95], v[196:197]
	v_pk_add_f32 v[88:89], v[88:89], v[208:209]
	v_pk_add_f32 v[90:91], v[90:91], v[210:211]
	v_mul_f32_e32 v214, v92, v92
	v_fmac_f32_e32 v214, v93, v93
	v_fmac_f32_e32 v214, v94, v94
	v_fmac_f32_e32 v214, v95, v95
	v_fmac_f32_e32 v214, v88, v88
	v_fmac_f32_e32 v214, v89, v89
	v_fmac_f32_e32 v214, v90, v90
	v_fmac_f32_e32 v214, v91, v91
	v_cvt_pk_bf16_f32 v136, v92, v93
	v_cvt_pk_bf16_f32 v137, v94, v95
	v_cvt_pk_bf16_f32 v138, v88, v89
	v_cvt_pk_bf16_f32 v139, v90, v91
	global_store_dwordx4 v229, v[136:139], s[4:5]
	v_lshlrev_b32_e32 v194, 16, v140
	v_and_b32_e32 v195, 0xffff0000, v140
	v_lshlrev_b32_e32 v196, 16, v141
	v_and_b32_e32 v197, 0xffff0000, v141
	v_lshlrev_b32_e32 v208, 16, v142
	v_and_b32_e32 v209, 0xffff0000, v142
	v_lshlrev_b32_e32 v210, 16, v143
	v_and_b32_e32 v211, 0xffff0000, v143
	v_pk_add_f32 v[84:85], v[84:85], v[194:195]
	v_pk_add_f32 v[86:87], v[86:87], v[196:197]
	v_pk_add_f32 v[80:81], v[80:81], v[208:209]
	v_pk_add_f32 v[82:83], v[82:83], v[210:211]
	v_mul_f32_e32 v222, v84, v84
	v_fmac_f32_e32 v222, v85, v85
	v_fmac_f32_e32 v222, v86, v86
	v_fmac_f32_e32 v222, v87, v87
	v_fmac_f32_e32 v222, v80, v80
	v_fmac_f32_e32 v222, v81, v81
	v_fmac_f32_e32 v222, v82, v82
	v_fmac_f32_e32 v222, v83, v83
	v_cvt_pk_bf16_f32 v140, v84, v85
	v_cvt_pk_bf16_f32 v141, v86, v87
	v_cvt_pk_bf16_f32 v142, v80, v81
	v_cvt_pk_bf16_f32 v143, v82, v83
	global_store_dwordx4 v229, v[140:143], s[4:5] offset:256
	s_waitcnt vmcnt(14)
	v_add_u32_e32 v229, 0x18000, v228
	v_lshlrev_b32_e32 v194, 16, v144
	v_and_b32_e32 v195, 0xffff0000, v144
	v_lshlrev_b32_e32 v196, 16, v145
	v_and_b32_e32 v197, 0xffff0000, v145
	v_lshlrev_b32_e32 v208, 16, v146
	v_and_b32_e32 v209, 0xffff0000, v146
	v_lshlrev_b32_e32 v210, 16, v147
	v_and_b32_e32 v211, 0xffff0000, v147
	v_pk_add_f32 v[76:77], v[76:77], v[194:195]
	v_pk_add_f32 v[78:79], v[78:79], v[196:197]
	v_pk_add_f32 v[72:73], v[72:73], v[208:209]
	v_pk_add_f32 v[74:75], v[74:75], v[210:211]
	v_mul_f32_e32 v215, v76, v76
	v_fmac_f32_e32 v215, v77, v77
	v_fmac_f32_e32 v215, v78, v78
	v_fmac_f32_e32 v215, v79, v79
	v_fmac_f32_e32 v215, v72, v72
	v_fmac_f32_e32 v215, v73, v73
	v_fmac_f32_e32 v215, v74, v74
	v_fmac_f32_e32 v215, v75, v75
	v_cvt_pk_bf16_f32 v144, v76, v77
	v_cvt_pk_bf16_f32 v145, v78, v79
	v_cvt_pk_bf16_f32 v146, v72, v73
	v_cvt_pk_bf16_f32 v147, v74, v75
	global_store_dwordx4 v229, v[144:147], s[4:5]
	v_lshlrev_b32_e32 v194, 16, v156
	v_and_b32_e32 v195, 0xffff0000, v156
	v_lshlrev_b32_e32 v196, 16, v157
	v_and_b32_e32 v197, 0xffff0000, v157
	v_lshlrev_b32_e32 v208, 16, v158
	v_and_b32_e32 v209, 0xffff0000, v158
	v_lshlrev_b32_e32 v210, 16, v159
	v_and_b32_e32 v211, 0xffff0000, v159
	v_pk_add_f32 v[68:69], v[68:69], v[194:195]
	v_pk_add_f32 v[70:71], v[70:71], v[196:197]
	v_pk_add_f32 v[64:65], v[64:65], v[208:209]
	v_pk_add_f32 v[66:67], v[66:67], v[210:211]
	v_mul_f32_e32 v223, v68, v68
	v_fmac_f32_e32 v223, v69, v69
	v_fmac_f32_e32 v223, v70, v70
	v_fmac_f32_e32 v223, v71, v71
	v_fmac_f32_e32 v223, v64, v64
	v_fmac_f32_e32 v223, v65, v65
	v_fmac_f32_e32 v223, v66, v66
	v_fmac_f32_e32 v223, v67, v67
	v_cvt_pk_bf16_f32 v156, v68, v69
	v_cvt_pk_bf16_f32 v157, v70, v71
	v_cvt_pk_bf16_f32 v158, v64, v65
	v_cvt_pk_bf16_f32 v159, v66, v67
	global_store_dwordx4 v229, v[156:159], s[4:5] offset:256
	s_waitcnt vmcnt(14)
	v_add_u32_e32 v229, 0x40000, v228
	v_lshlrev_b32_e32 v194, 16, v160
	v_and_b32_e32 v195, 0xffff0000, v160
	v_lshlrev_b32_e32 v196, 16, v161
	v_and_b32_e32 v197, 0xffff0000, v161
	v_lshlrev_b32_e32 v208, 16, v162
	v_and_b32_e32 v209, 0xffff0000, v162
	v_lshlrev_b32_e32 v210, 16, v163
	v_and_b32_e32 v211, 0xffff0000, v163
	v_pk_add_f32 v[60:61], v[60:61], v[194:195]
	v_pk_add_f32 v[62:63], v[62:63], v[196:197]
	v_pk_add_f32 v[56:57], v[56:57], v[208:209]
	v_pk_add_f32 v[58:59], v[58:59], v[210:211]
	v_mul_f32_e32 v216, v60, v60
	v_fmac_f32_e32 v216, v61, v61
	v_fmac_f32_e32 v216, v62, v62
	v_fmac_f32_e32 v216, v63, v63
	v_fmac_f32_e32 v216, v56, v56
	v_fmac_f32_e32 v216, v57, v57
	v_fmac_f32_e32 v216, v58, v58
	v_fmac_f32_e32 v216, v59, v59
	v_cvt_pk_bf16_f32 v160, v60, v61
	v_cvt_pk_bf16_f32 v161, v62, v63
	v_cvt_pk_bf16_f32 v162, v56, v57
	v_cvt_pk_bf16_f32 v163, v58, v59
	global_store_dwordx4 v229, v[160:163], s[4:5]
	v_lshlrev_b32_e32 v194, 16, v164
	v_and_b32_e32 v195, 0xffff0000, v164
	v_lshlrev_b32_e32 v196, 16, v165
	v_and_b32_e32 v197, 0xffff0000, v165
	v_lshlrev_b32_e32 v208, 16, v166
	v_and_b32_e32 v209, 0xffff0000, v166
	v_lshlrev_b32_e32 v210, 16, v167
	v_and_b32_e32 v211, 0xffff0000, v167
	v_pk_add_f32 v[52:53], v[52:53], v[194:195]
	v_pk_add_f32 v[54:55], v[54:55], v[196:197]
	v_pk_add_f32 v[48:49], v[48:49], v[208:209]
	v_pk_add_f32 v[50:51], v[50:51], v[210:211]
	v_mul_f32_e32 v224, v52, v52
	v_fmac_f32_e32 v224, v53, v53
	v_fmac_f32_e32 v224, v54, v54
	v_fmac_f32_e32 v224, v55, v55
	v_fmac_f32_e32 v224, v48, v48
	v_fmac_f32_e32 v224, v49, v49
	v_fmac_f32_e32 v224, v50, v50
	v_fmac_f32_e32 v224, v51, v51
	v_cvt_pk_bf16_f32 v164, v52, v53
	v_cvt_pk_bf16_f32 v165, v54, v55
	v_cvt_pk_bf16_f32 v166, v48, v49
	v_cvt_pk_bf16_f32 v167, v50, v51
	global_store_dwordx4 v229, v[164:167], s[4:5] offset:256
	s_waitcnt vmcnt(14)
; __device__ __forceinline__ unsigned cvt_pk_bf16(float lo, float hi) { unsigned r; asm volatile("v_cvt_pk_bf16_f32 %0, %1, %2" : "=v"(r) : "v"(lo), "v"(hi)); return r; }
;     __device__ __forceinline__ void operator()(const f32x4 (&acc)[2][2][4][2], const Unit& u, int wr, int wc, int fr, int fq) const {
;     ...
;             for (int m = 0; m < 4; ++m) { const int row = row0 + ai * HALF + m * 16; const size_t off = (size_t)row * 1024 + col0; float ss = 0.f;
; #pragma unroll
;                 for (int bj = 0; bj < 2; ++bj) {
;                     const u32x4 b = bw[ai][m][bj];
;                     const f32x4 b0 = (f32x4){__uint_as_float(b.x << 16), __uint_as_float(b.x & 0xffff0000u), __uint_as_float(b.y << 16), __uint_as_float(b.y & 0xffff0000u)};
;                     const f32x4 b1 = (f32x4){__uint_as_float(b.z << 16), __uint_as_float(b.z & 0xffff0000u), __uint_as_float(b.w << 16), __uint_as_float(b.w & 0xffff0000u)};
;                     const f32x4 v0 = acc[ai][bj][m][0] + b0, v1 = acc[ai][bj][m][1] + b1;
;                     ss += (v0[0] * v0[0] + v0[1] * v0[1]) + (v0[2] * v0[2] + v0[3] * v0[3]) + (v1[0] * v1[0] + v1[1] * v1[1]) + (v1[2] * v1[2] + v1[3] * v1[3]);
;                     u32x4 w; w.x = cvt_pk_bf16(v0[0], v0[1]); w.y = cvt_pk_bf16(v0[2], v0[3]); w.z = cvt_pk_bf16(v1[0], v1[1]); w.w = cvt_pk_bf16(v1[2], v1[3]);
;                     *(u32x4*)(hb + off + bj * HALF) = w; }
	v_add_u32_e32 v229, 0x48000, v228
	v_lshlrev_b32_e32 v194, 16, v168
	v_and_b32_e32 v195, 0xffff0000, v168
	v_lshlrev_b32_e32 v196, 16, v169
	v_and_b32_e32 v197, 0xffff0000, v169
	v_lshlrev_b32_e32 v208, 16, v170
	v_and_b32_e32 v209, 0xffff0000, v170
	v_lshlrev_b32_e32 v210, 16, v171
	v_and_b32_e32 v211, 0xffff0000, v171
	v_pk_add_f32 v[44:45], v[44:45], v[194:195]
	v_pk_add_f32 v[46:47], v[46:47], v[196:197]
	v_pk_add_f32 v[40:41], v[40:41], v[208:209]
	v_pk_add_f32 v[42:43], v[42:43], v[210:211]
	v_mul_f32_e32 v217, v44, v44
	v_fmac_f32_e32 v217, v45, v45
	v_fmac_f32_e32 v217, v46, v46
	v_fmac_f32_e32 v217, v47, v47
	v_fmac_f32_e32 v217, v40, v40
	v_fmac_f32_e32 v217, v41, v41
	v_fmac_f32_e32 v217, v42, v42
	v_fmac_f32_e32 v217, v43, v43
	v_cvt_pk_bf16_f32 v168, v44, v45
	v_cvt_pk_bf16_f32 v169, v46, v47
	v_cvt_pk_bf16_f32 v170, v40, v41
	v_cvt_pk_bf16_f32 v171, v42, v43
	global_store_dwordx4 v229, v[168:171], s[4:5]
	v_lshlrev_b32_e32 v194, 16, v172
	v_and_b32_e32 v195, 0xffff0000, v172
	v_lshlrev_b32_e32 v196, 16, v173
	v_and_b32_e32 v197, 0xffff0000, v173
	v_lshlrev_b32_e32 v208, 16, v174
	v_and_b32_e32 v209, 0xffff0000, v174
	v_lshlrev_b32_e32 v210, 16, v175
	v_and_b32_e32 v211, 0xffff0000, v175
	v_pk_add_f32 v[36:37], v[36:37], v[194:195]
	v_pk_add_f32 v[38:39], v[38:39], v[196:197]
	v_pk_add_f32 v[32:33], v[32:33], v[208:209]
	v_pk_add_f32 v[34:35], v[34:35], v[210:211]
	v_mul_f32_e32 v225, v36, v36
	v_fmac_f32_e32 v225, v37, v37
	v_fmac_f32_e32 v225, v38, v38
	v_fmac_f32_e32 v225, v39, v39
	v_fmac_f32_e32 v225, v32, v32
	v_fmac_f32_e32 v225, v33, v33
	v_fmac_f32_e32 v225, v34, v34
	v_fmac_f32_e32 v225, v35, v35
	v_cvt_pk_bf16_f32 v172, v36, v37
	v_cvt_pk_bf16_f32 v173, v38, v39
	v_cvt_pk_bf16_f32 v174, v32, v33
	v_cvt_pk_bf16_f32 v175, v34, v35
	global_store_dwordx4 v229, v[172:175], s[4:5] offset:256
	s_waitcnt vmcnt(14)
	v_add_u32_e32 v229, 0x50000, v228
	v_lshlrev_b32_e32 v194, 16, v176
	v_and_b32_e32 v195, 0xffff0000, v176
	v_lshlrev_b32_e32 v196, 16, v177
	v_and_b32_e32 v197, 0xffff0000, v177
	v_lshlrev_b32_e32 v208, 16, v178
	v_and_b32_e32 v209, 0xffff0000, v178
	v_lshlrev_b32_e32 v210, 16, v179
	v_and_b32_e32 v211, 0xffff0000, v179
	v_pk_add_f32 v[28:29], v[28:29], v[194:195]
	v_pk_add_f32 v[30:31], v[30:31], v[196:197]
	v_pk_add_f32 v[24:25], v[24:25], v[208:209]
	v_pk_add_f32 v[26:27], v[26:27], v[210:211]
	v_mul_f32_e32 v218, v28, v28
	v_fmac_f32_e32 v218, v29, v29
	v_fmac_f32_e32 v218, v30, v30
	v_fmac_f32_e32 v218, v31, v31
	v_fmac_f32_e32 v218, v24, v24
	v_fmac_f32_e32 v218, v25, v25
	v_fmac_f32_e32 v218, v26, v26
	v_fmac_f32_e32 v218, v27, v27
	v_cvt_pk_bf16_f32 v176, v28, v29
	v_cvt_pk_bf16_f32 v177, v30, v31
	v_cvt_pk_bf16_f32 v178, v24, v25
	v_cvt_pk_bf16_f32 v179, v26, v27
	global_store_dwordx4 v229, v[176:179], s[4:5]
	v_lshlrev_b32_e32 v194, 16, v180
	v_and_b32_e32 v195, 0xffff0000, v180
	v_lshlrev_b32_e32 v196, 16, v181
	v_and_b32_e32 v197, 0xffff0000, v181
	v_lshlrev_b32_e32 v208, 16, v182
	v_and_b32_e32 v209, 0xffff0000, v182
	v_lshlrev_b32_e32 v210, 16, v183
	v_and_b32_e32 v211, 0xffff0000, v183
	v_pk_add_f32 v[20:21], v[20:21], v[194:195]
	v_pk_add_f32 v[22:23], v[22:23], v[196:197]
	v_pk_add_f32 v[16:17], v[16:17], v[208:209]
	v_pk_add_f32 v[18:19], v[18:19], v[210:211]
	v_mul_f32_e32 v226, v20, v20
	v_fmac_f32_e32 v226, v21, v21
	v_fmac_f32_e32 v226, v22, v22
	v_fmac_f32_e32 v226, v23, v23
	v_fmac_f32_e32 v226, v16, v16
	v_fmac_f32_e32 v226, v17, v17
	v_fmac_f32_e32 v226, v18, v18
	v_fmac_f32_e32 v226, v19, v19
	v_cvt_pk_bf16_f32 v180, v20, v21
	v_cvt_pk_bf16_f32 v181, v22, v23
	v_cvt_pk_bf16_f32 v182, v16, v17
	v_cvt_pk_bf16_f32 v183, v18, v19
	global_store_dwordx4 v229, v[180:183], s[4:5] offset:256
	s_waitcnt vmcnt(14)
; __device__ __forceinline__ unsigned cvt_pk_bf16(float lo, float hi) { unsigned r; asm volatile("v_cvt_pk_bf16_f32 %0, %1, %2" : "=v"(r) : "v"(lo), "v"(hi)); return r; }
;     __device__ __forceinline__ void operator()(const f32x4 (&acc)[2][2][4][2], const Unit& u, int wr, int wc, int fr, int fq) const {
;     ...
;             for (int m = 0; m < 4; ++m) { const int row = row0 + ai * HALF + m * 16; const size_t off = (size_t)row * 1024 + col0; float ss = 0.f;
; #pragma unroll
;                 for (int bj = 0; bj < 2; ++bj) {
;                     const u32x4 b = bw[ai][m][bj];
;                     const f32x4 b0 = (f32x4){__uint_as_float(b.x << 16), __uint_as_float(b.x & 0xffff0000u), __uint_as_float(b.y << 16), __uint_as_float(b.y & 0xffff0000u)};
;                     const f32x4 b1 = (f32x4){__uint_as_float(b.z << 16), __uint_as_float(b.z & 0xffff0000u), __uint_as_float(b.w << 16), __uint_as_float(b.w & 0xffff0000u)};
;                     const f32x4 v0 = acc[ai][bj][m][0] + b0, v1 = acc[ai][bj][m][1] + b1;
;                     ss += (v0[0] * v0[0] + v0[1] * v0[1]) + (v0[2] * v0[2] + v0[3] * v0[3]) + (v1[0] * v1[0] + v1[1] * v1[1]) + (v1[2] * v1[2] + v1[3] * v1[3]);
;                     u32x4 w; w.x = cvt_pk_bf16(v0[0], v0[1]); w.y = cvt_pk_bf16(v0[2], v0[3]); w.z = cvt_pk_bf16(v1[0], v1[1]); w.w = cvt_pk_bf16(v1[2], v1[3]);
;                     *(u32x4*)(hb + off + bj * HALF) = w; }
;                 ss += __shfl_xor(ss, 16); ss += __shfl_xor(ss, 32);
;                 if (fq == 0) slots[(size_t)row * 16 + u.pn * 4 + wc] = ss; }
	v_add_u32_e32 v229, 0x58000, v228
	v_lshlrev_b32_e32 v194, 16, v184
	v_and_b32_e32 v195, 0xffff0000, v184
	v_lshlrev_b32_e32 v196, 16, v185
	v_and_b32_e32 v197, 0xffff0000, v185
	v_lshlrev_b32_e32 v208, 16, v186
	v_and_b32_e32 v209, 0xffff0000, v186
	v_lshlrev_b32_e32 v210, 16, v187
	v_and_b32_e32 v211, 0xffff0000, v187
	v_pk_add_f32 v[12:13], v[12:13], v[194:195]
	v_pk_add_f32 v[14:15], v[14:15], v[196:197]
	v_pk_add_f32 v[8:9], v[8:9], v[208:209]
	v_pk_add_f32 v[10:11], v[10:11], v[210:211]
	v_mul_f32_e32 v219, v12, v12
	v_fmac_f32_e32 v219, v13, v13
	v_fmac_f32_e32 v219, v14, v14
	v_fmac_f32_e32 v219, v15, v15
	v_fmac_f32_e32 v219, v8, v8
	v_fmac_f32_e32 v219, v9, v9
	v_fmac_f32_e32 v219, v10, v10
	v_fmac_f32_e32 v219, v11, v11
	v_cvt_pk_bf16_f32 v184, v12, v13
	v_cvt_pk_bf16_f32 v185, v14, v15
	v_cvt_pk_bf16_f32 v186, v8, v9
	v_cvt_pk_bf16_f32 v187, v10, v11
	global_store_dwordx4 v229, v[184:187], s[4:5]
	v_lshlrev_b32_e32 v194, 16, v188
	v_and_b32_e32 v195, 0xffff0000, v188
	v_lshlrev_b32_e32 v196, 16, v189
	v_and_b32_e32 v197, 0xffff0000, v189
	v_lshlrev_b32_e32 v208, 16, v190
	v_and_b32_e32 v209, 0xffff0000, v190
	v_lshlrev_b32_e32 v210, 16, v191
	v_and_b32_e32 v211, 0xffff0000, v191
	v_pk_add_f32 v[4:5], v[4:5], v[194:195]
	v_pk_add_f32 v[6:7], v[6:7], v[196:197]
	v_pk_add_f32 v[0:1], v[0:1], v[208:209]
	v_pk_add_f32 v[2:3], v[2:3], v[210:211]
	v_mul_f32_e32 v227, v4, v4
	v_fmac_f32_e32 v227, v5, v5
	v_fmac_f32_e32 v227, v6, v6
	v_fmac_f32_e32 v227, v7, v7
	v_fmac_f32_e32 v227, v0, v0
	v_fmac_f32_e32 v227, v1, v1
	v_fmac_f32_e32 v227, v2, v2
	v_fmac_f32_e32 v227, v3, v3
	v_cvt_pk_bf16_f32 v188, v4, v5
	v_cvt_pk_bf16_f32 v189, v6, v7
	v_cvt_pk_bf16_f32 v190, v0, v1
	v_cvt_pk_bf16_f32 v191, v2, v3
	global_store_dwordx4 v229, v[188:191], s[4:5] offset:256
	v_add_f32_e32 v212, v212, v220
	v_add_f32_e32 v213, v213, v221
	v_add_f32_e32 v214, v214, v222
	v_add_f32_e32 v215, v215, v223
	v_add_f32_e32 v216, v216, v224
	v_add_f32_e32 v217, v217, v225
	v_add_f32_e32 v218, v218, v226
	v_add_f32_e32 v219, v219, v227
	ds_bpermute_b32 v232, v230, v212
	ds_bpermute_b32 v233, v230, v213
	ds_bpermute_b32 v234, v230, v214
	ds_bpermute_b32 v235, v230, v215
	ds_bpermute_b32 v236, v230, v216
	ds_bpermute_b32 v237, v230, v217
	ds_bpermute_b32 v238, v230, v218
	ds_bpermute_b32 v239, v230, v219
	s_waitcnt lgkmcnt(0)
	v_add_f32_e32 v212, v212, v232
	v_add_f32_e32 v213, v213, v233
	v_add_f32_e32 v214, v214, v234
	v_add_f32_e32 v215, v215, v235
	v_add_f32_e32 v216, v216, v236
	v_add_f32_e32 v217, v217, v237
	v_add_f32_e32 v218, v218, v238
	v_add_f32_e32 v219, v219, v239
	ds_bpermute_b32 v232, v231, v212
	ds_bpermute_b32 v233, v231, v213
	ds_bpermute_b32 v234, v231, v214
	ds_bpermute_b32 v235, v231, v215
	ds_bpermute_b32 v236, v231, v216
	ds_bpermute_b32 v237, v231, v217
	ds_bpermute_b32 v238, v231, v218
	ds_bpermute_b32 v239, v231, v219
	s_waitcnt lgkmcnt(0)
	v_add_f32_e32 v212, v212, v232
	v_add_f32_e32 v213, v213, v233
	v_add_f32_e32 v214, v214, v234
	v_add_f32_e32 v215, v215, v235
	v_add_f32_e32 v216, v216, v236
	v_add_f32_e32 v217, v217, v237
	v_add_f32_e32 v218, v218, v238
	v_add_f32_e32 v219, v219, v239
	s_and_saveexec_b64 s[20:21], s[38:39]
	global_store_dword v240, v212, s[8:9]
	global_store_dword v240, v213, s[8:9] offset:1024
	global_store_dword v240, v214, s[8:9] offset:2048
	global_store_dword v240, v215, s[8:9] offset:3072
	global_store_dword v241, v216, s[8:9]
	global_store_dword v241, v217, s[8:9] offset:1024
	global_store_dword v241, v218, s[8:9] offset:2048
	global_store_dword v241, v219, s[8:9] offset:3072
	s_or_b64 exec, exec, s[20:21]
	s_movk_i32 s29, 0x1600
	s_and_b64 vcc, exec, s[40:41]
	s_mov_b64 s[16:17], -1
	s_cbranch_vccnz .LBB0_1019
	s_andn2_b64 vcc, exec, s[0:1]
	s_cbranch_vccnz .LBB0_1018
	s_barrier
	s_branch .LBB0_1018
